# GEMM main loop: per-segment priority flips removed, one static priority raise for waves 0-3
# speedup vs baseline: 1.0801x; 1.0092x over previous
; #define PG8_STAGE(bufoff, gbase, voff) do { _Pragma("unroll") for (int _i = 0; _i < 2; ++_i) \
;         __builtin_amdgcn_global_load_lds((const unsigned*)((const char*)(gbase) + (voff)[_i]), (LAS unsigned*)(lds + (bufoff) + ldsw + _i * 8192), 16, 0, 0); } while (0)
; #define PG8_WAIT_V(n) asm volatile("s_waitcnt vmcnt(" #n ")" ::: "memory")
; #define PG8_BAR __builtin_amdgcn_s_barrier()
; template <class Epi>
; __device__ __forceinline__ void gemm_phase(LAS unsigned char* lds, const Gemm g, const StaticOrder& S, const Epi& E) {
;     ...
;     PG8_STAGE(PG8_SB(0, 0), cB, voffB); PG8_STAGE(PG8_SA(0, 0), cA, voffA); PG8_STAGE(PG8_SB(0, 1), cB + hstepB, voffB); PG8_STAGE(PG8_SA(0, 1), cA + hstepA, voffA);
;     if (wr == 1) PG8_BAR;
;     PG8_WAIT_V(4); PG8_BAR;
;     PG8_STAGE(PG8_SB(1, 0), cB + kstep, voffB); PG8_STAGE(PG8_SA(1, 0), cA + kstep, voffA); PG8_STAGE(PG8_SB(1, 1), cB + hstepB + kstep, voffB);
;     PG8_WAIT_V(6); PG8_BAR;
;     for (;;) {
;         const bool has_next = S.next(ui + 1, nxt);
.LBB0_107:
	s_setprio 0
	s_cmpk_ge_u32 s79, 0x100
	s_cbranch_scc1 .Lprio_done
	s_setprio 1

; #define PG8_STAGE(bufoff, gbase, voff) do { _Pragma("unroll") for (int _i = 0; _i < 2; ++_i) \
;         __builtin_amdgcn_global_load_lds((const unsigned*)((const char*)(gbase) + (voff)[_i]), (LAS unsigned*)(lds + (bufoff) + ldsw + _i * 8192), 16, 0, 0); } while (0)
; #define PG8_LDA(dst, b, h) do { _Pragma("unroll") for (int m = 0; m < 4; ++m) _Pragma("unroll") for (int k = 0; k < 2; ++k) dst[m][k] = *(const LAS bf16x8*)(lds + PG8_SA(b, h) + aoff + m * 2048 + k * 1024); } while (0)
; #define PG8_LDB(dst, b, h) do { _Pragma("unroll") for (int n = 0; n < 2; ++n) _Pragma("unroll") for (int k = 0; k < 2; ++k) dst[n][k] = *(const LAS bf16x8*)(lds + PG8_SB(b, h) + boff + n * 2048 + k * 1024); } while (0)
; #define PG8_MMA(ai, bj, At, Bt) do { __builtin_amdgcn_s_setprio(1); _Pragma("unroll") for (int m = 0; m < 4; ++m) _Pragma("unroll") for (int n = 0; n < 2; ++n) _Pragma("unroll") for (int k = 0; k < 2; ++k) \
;         acc[ai][bj][m][n] = __builtin_amdgcn_mfma_f32_16x16x32_bf16(Bt[n][k], At[m][k], acc[ai][bj][m][n], 0, 0, 0); __builtin_amdgcn_s_setprio(0); } while (0)
; #define PG8_WAIT_L(n) asm volatile("s_waitcnt lgkmcnt(" #n ")" ::: "memory")
; #define PG8_BAR __builtin_amdgcn_s_barrier()
; #define PG8_SCHED __builtin_amdgcn_sched_barrier(0)
; template <class Epi>
; __device__ __forceinline__ void gemm_phase(LAS unsigned char* lds, const Gemm g, const StaticOrder& S, const Epi& E) {
;     ...
;             PG8_LDB(B0, 0, 0); PG8_SCHED; PG8_LDA(At, 0, 0); PG8_STAGE(PG8_SA(1, 1), a1 + hstepA, voffA);
;             PG8_WAIT_L(8); PG8_BAR; PG8_WAIT_L(0); PG8_MMA(0, 0, At, B0); PG8_BAR; PG8_SCHED;
;             PG8_LDB(B1, 0, 1); PG8_STAGE(PG8_SB(0, 0), b2, voffB);
;             PG8_BAR; PG8_WAIT_L(0); PG8_MMA(0, 1, At, B1); PG8_BAR;
;             PG8_LDA(At, 0, 1); PG8_STAGE(PG8_SA(0, 0), a2, voffA);
;             PG8_BAR; PG8_WAIT_L(0); PG8_MMA(1, 0, At, B0); PG8_BAR; PG8_SCHED;
.LBB0_116:
	s_add_i32 s35, s44, 2
	s_add_u32 s46, s36, 0x80
	s_addc_u32 s45, s37, 0
	s_cmp_eq_u32 s17, s44
	s_cselect_b32 s45, s29, s45
	s_cselect_b32 s44, s28, s46
	s_cselect_b32 s47, s31, s70
	s_cselect_b32 s46, s30, s69
	s_add_i32 s71, 0, 0x10000
	v_add_u32_e32 v142, s71, v225
	ds_read_b128 v[130:133], v142
	ds_read_b128 v[134:137], v142 offset:1024
	ds_read_b128 v[138:141], v142 offset:2048
	ds_read_b128 v[142:145], v142 offset:3072
	v_lshl_add_u64 v[166:167], s[36:37], 0, v[186:187]
	s_add_i32 m0, s39, 0xc000
	ds_read_b128 v[146:149], v228
	ds_read_b128 v[150:153], v228 offset:1024
	ds_read_b128 v[154:157], v228 offset:2048
	ds_read_b128 v[158:161], v228 offset:3072
	ds_read_b128 v[162:165], v228 offset:4096
	ds_read_b128 v[190:193], v228 offset:5120
	ds_read_b128 v[194:197], v228 offset:6144
	ds_read_b128 v[198:201], v228 offset:7168
	global_load_lds_dwordx4 v[166:167], off
	v_lshl_add_u64 v[166:167], s[36:37], 0, v[188:189]
	s_add_i32 m0, s39, 0xe000
	s_nop 0
	global_load_lds_dwordx4 v[166:167], off
	s_waitcnt lgkmcnt(8)
	s_barrier
	s_waitcnt lgkmcnt(0)
	s_waitcnt lgkmcnt(0)
	v_mfma_f32_16x16x32_bf16 v[124:127], v[130:133], v[146:149], v[124:127]
	v_mfma_f32_16x16x32_bf16 v[120:123], v[138:141], v[146:149], v[120:123]
	v_mfma_f32_16x16x32_bf16 v[112:115], v[130:133], v[154:157], v[112:115]
	v_mfma_f32_16x16x32_bf16 v[104:107], v[138:141], v[154:157], v[104:107]
	v_mfma_f32_16x16x32_bf16 v[96:99], v[130:133], v[162:165], v[96:99]
	v_mfma_f32_16x16x32_bf16 v[88:91], v[138:141], v[162:165], v[88:91]
	v_mfma_f32_16x16x32_bf16 v[80:83], v[130:133], v[194:197], v[80:83]
	v_mfma_f32_16x16x32_bf16 v[72:75], v[138:141], v[194:197], v[72:75]
	v_mfma_f32_16x16x32_bf16 v[124:127], v[134:137], v[150:153], v[124:127]
	v_mfma_f32_16x16x32_bf16 v[120:123], v[142:145], v[150:153], v[120:123]
	v_mfma_f32_16x16x32_bf16 v[112:115], v[134:137], v[158:161], v[112:115]
	v_mfma_f32_16x16x32_bf16 v[104:107], v[142:145], v[158:161], v[104:107]
	v_mfma_f32_16x16x32_bf16 v[96:99], v[134:137], v[190:193], v[96:99]
	v_mfma_f32_16x16x32_bf16 v[88:91], v[142:145], v[190:193], v[88:91]
	v_mfma_f32_16x16x32_bf16 v[80:83], v[134:137], v[198:201], v[80:83]
	v_mfma_f32_16x16x32_bf16 v[72:75], v[142:145], v[198:201], v[72:75]
	s_barrier
	s_add_i32 s72, 0, 0x14000
	v_add_u32_e32 v166, s72, v225
	s_add_i32 s71, s71, s57
	ds_read_b128 v[202:205], v166
	ds_read_b128 v[230:233], v166 offset:1024
	ds_read_b128 v[234:237], v166 offset:2048
	ds_read_b128 v[238:241], v166 offset:3072
	v_lshl_add_u64 v[166:167], s[46:47], 0, v[168:169]
	s_mov_b32 m0, s71
	v_lshl_add_u64 v[206:207], s[46:47], 0, v[178:179]
	global_load_lds_dwordx4 v[166:167], off
	s_add_i32 m0, s71, 0x2000
	s_nop 0
	global_load_lds_dwordx4 v[206:207], off
	s_barrier
	s_waitcnt lgkmcnt(0)
	s_waitcnt lgkmcnt(0)
	v_mfma_f32_16x16x32_bf16 v[116:119], v[202:205], v[146:149], v[116:119]
	v_mfma_f32_16x16x32_bf16 v[108:111], v[234:237], v[146:149], v[108:111]
	v_mfma_f32_16x16x32_bf16 v[100:103], v[202:205], v[154:157], v[100:103]
	v_mfma_f32_16x16x32_bf16 v[92:95], v[234:237], v[154:157], v[92:95]
	v_mfma_f32_16x16x32_bf16 v[84:87], v[202:205], v[162:165], v[84:87]
	v_mfma_f32_16x16x32_bf16 v[76:79], v[234:237], v[162:165], v[76:79]
	v_mfma_f32_16x16x32_bf16 v[68:71], v[202:205], v[194:197], v[68:71]
	v_mfma_f32_16x16x32_bf16 v[64:67], v[234:237], v[194:197], v[64:67]
	v_mfma_f32_16x16x32_bf16 v[116:119], v[230:233], v[150:153], v[116:119]
	v_mfma_f32_16x16x32_bf16 v[108:111], v[238:241], v[150:153], v[108:111]
	v_mfma_f32_16x16x32_bf16 v[100:103], v[230:233], v[158:161], v[100:103]
	v_mfma_f32_16x16x32_bf16 v[92:95], v[238:241], v[158:161], v[92:95]
	v_mfma_f32_16x16x32_bf16 v[84:87], v[230:233], v[190:193], v[84:87]
	v_mfma_f32_16x16x32_bf16 v[76:79], v[238:241], v[190:193], v[76:79]
	v_mfma_f32_16x16x32_bf16 v[68:71], v[230:233], v[198:201], v[68:71]
	v_mfma_f32_16x16x32_bf16 v[64:67], v[238:241], v[198:201], v[64:67]
	s_mov_b32 m0, s39
	v_lshl_add_u64 v[242:243], s[44:45], 0, v[174:175]
	s_barrier
	ds_read_b128 v[146:149], v228 offset:16384
	ds_read_b128 v[150:153], v228 offset:17408
	ds_read_b128 v[154:157], v228 offset:18432
	ds_read_b128 v[158:161], v228 offset:19456
	ds_read_b128 v[162:165], v228 offset:20480
	ds_read_b128 v[190:193], v228 offset:21504
	ds_read_b128 v[194:197], v228 offset:22528
	ds_read_b128 v[198:201], v228 offset:23552
	global_load_lds_dwordx4 v[242:243], off
	v_lshl_add_u64 v[244:245], s[44:45], 0, v[176:177]
	s_mov_b32 m0, s54
	s_nop 0
	global_load_lds_dwordx4 v[244:245], off
	s_barrier
	s_waitcnt lgkmcnt(0)
	s_waitcnt lgkmcnt(0)
	v_mfma_f32_16x16x32_bf16 v[60:63], v[130:133], v[146:149], v[60:63]
	v_mfma_f32_16x16x32_bf16 v[56:59], v[138:141], v[146:149], v[56:59]
	v_mfma_f32_16x16x32_bf16 v[52:55], v[130:133], v[154:157], v[52:55]
	v_mfma_f32_16x16x32_bf16 v[44:47], v[138:141], v[154:157], v[44:47]
	v_mfma_f32_16x16x32_bf16 v[36:39], v[130:133], v[162:165], v[36:39]
	v_mfma_f32_16x16x32_bf16 v[28:31], v[138:141], v[162:165], v[28:31]
	v_mfma_f32_16x16x32_bf16 v[20:23], v[130:133], v[194:197], v[20:23]
	v_mfma_f32_16x16x32_bf16 v[12:15], v[138:141], v[194:197], v[12:15]
	v_mfma_f32_16x16x32_bf16 v[60:63], v[134:137], v[150:153], v[60:63]
	v_mfma_f32_16x16x32_bf16 v[56:59], v[142:145], v[150:153], v[56:59]
	v_mfma_f32_16x16x32_bf16 v[52:55], v[134:137], v[158:161], v[52:55]
	v_mfma_f32_16x16x32_bf16 v[44:47], v[142:145], v[158:161], v[44:47]
	v_mfma_f32_16x16x32_bf16 v[36:39], v[134:137], v[190:193], v[36:39]
	v_mfma_f32_16x16x32_bf16 v[28:31], v[142:145], v[190:193], v[28:31]
	v_mfma_f32_16x16x32_bf16 v[20:23], v[134:137], v[198:201], v[20:23]
	v_mfma_f32_16x16x32_bf16 v[12:15], v[142:145], v[198:201], v[12:15]
	s_barrier
; #define PG8_STAGE(bufoff, gbase, voff) do { _Pragma("unroll") for (int _i = 0; _i < 2; ++_i) \
;         __builtin_amdgcn_global_load_lds((const unsigned*)((const char*)(gbase) + (voff)[_i]), (LAS unsigned*)(lds + (bufoff) + ldsw + _i * 8192), 16, 0, 0); } while (0)
; #define PG8_LDA(dst, b, h) do { _Pragma("unroll") for (int m = 0; m < 4; ++m) _Pragma("unroll") for (int k = 0; k < 2; ++k) dst[m][k] = *(const LAS bf16x8*)(lds + PG8_SA(b, h) + aoff + m * 2048 + k * 1024); } while (0)
; #define PG8_LDB(dst, b, h) do { _Pragma("unroll") for (int n = 0; n < 2; ++n) _Pragma("unroll") for (int k = 0; k < 2; ++k) dst[n][k] = *(const LAS bf16x8*)(lds + PG8_SB(b, h) + boff + n * 2048 + k * 1024); } while (0)
; #define PG8_MMA(ai, bj, At, Bt) do { __builtin_amdgcn_s_setprio(1); _Pragma("unroll") for (int m = 0; m < 4; ++m) _Pragma("unroll") for (int n = 0; n < 2; ++n) _Pragma("unroll") for (int k = 0; k < 2; ++k) \
;         acc[ai][bj][m][n] = __builtin_amdgcn_mfma_f32_16x16x32_bf16(Bt[n][k], At[m][k], acc[ai][bj][m][n], 0, 0, 0); __builtin_amdgcn_s_setprio(0); } while (0)
; #define PG8_WAIT_V(n) asm volatile("s_waitcnt vmcnt(" #n ")" ::: "memory")
; #define PG8_WAIT_L(n) asm volatile("s_waitcnt lgkmcnt(" #n ")" ::: "memory")
; #define PG8_BAR __builtin_amdgcn_s_barrier()
; #define PG8_SCHED __builtin_amdgcn_sched_barrier(0)
; template <class Epi>
; __device__ __forceinline__ void gemm_phase(LAS unsigned char* lds, const Gemm g, const StaticOrder& S, const Epi& E) {
;     ...
;             PG8_STAGE(PG8_SB(0, 1), b2 + hstepB, voffB);
;             PG8_WAIT_V(6); PG8_BAR; PG8_MMA(1, 1, At, B1); PG8_BAR;
;             PG8_LDB(B0, 1, 0); PG8_SCHED; PG8_LDA(At, 1, 0); PG8_STAGE(PG8_SA(0, 1), a2 + hstepA, voffA);
;             PG8_WAIT_L(8); PG8_BAR; PG8_WAIT_L(0); PG8_MMA(0, 0, At, B0); PG8_BAR; PG8_SCHED;
;             PG8_LDB(B1, 1, 1); PG8_STAGE(PG8_SB(1, 0), b3, voffB);
	s_add_u32 s46, s46, s50
	s_addc_u32 s47, s47, 0
	s_add_i32 s71, s72, s57
	v_lshl_add_u64 v[246:247], s[46:47], 0, v[168:169]
	s_mov_b32 m0, s71
	v_lshl_add_u64 v[248:249], s[46:47], 0, v[178:179]
	global_load_lds_dwordx4 v[246:247], off
	s_add_i32 m0, s71, 0x2000
	s_nop 0
	global_load_lds_dwordx4 v[248:249], off
	s_waitcnt vmcnt(6)
	s_barrier
	v_mfma_f32_16x16x32_bf16 v[48:51], v[202:205], v[146:149], v[48:51]
	v_mfma_f32_16x16x32_bf16 v[40:43], v[234:237], v[146:149], v[40:43]
	v_mfma_f32_16x16x32_bf16 v[32:35], v[202:205], v[154:157], v[32:35]
	v_mfma_f32_16x16x32_bf16 v[24:27], v[234:237], v[154:157], v[24:27]
	v_mfma_f32_16x16x32_bf16 v[16:19], v[202:205], v[162:165], v[16:19]
	v_mfma_f32_16x16x32_bf16 v[8:11], v[234:237], v[162:165], v[8:11]
	v_mfma_f32_16x16x32_bf16 v[4:7], v[202:205], v[194:197], v[4:7]
	v_mfma_f32_16x16x32_bf16 v[0:3], v[234:237], v[194:197], v[0:3]
	v_mfma_f32_16x16x32_bf16 v[48:51], v[230:233], v[150:153], v[48:51]
	v_mfma_f32_16x16x32_bf16 v[40:43], v[238:241], v[150:153], v[40:43]
	v_mfma_f32_16x16x32_bf16 v[32:35], v[230:233], v[158:161], v[32:35]
	v_mfma_f32_16x16x32_bf16 v[24:27], v[238:241], v[158:161], v[24:27]
	v_mfma_f32_16x16x32_bf16 v[16:19], v[230:233], v[190:193], v[16:19]
	v_mfma_f32_16x16x32_bf16 v[8:11], v[238:241], v[190:193], v[8:11]
	v_mfma_f32_16x16x32_bf16 v[4:7], v[230:233], v[198:201], v[4:7]
	v_mfma_f32_16x16x32_bf16 v[0:3], v[238:241], v[198:201], v[0:3]
	s_add_i32 s46, 0, 0x18000
	v_add_u32_e32 v142, s46, v225
	s_barrier
	ds_read_b128 v[130:133], v142
	ds_read_b128 v[134:137], v142 offset:1024
	ds_read_b128 v[138:141], v142 offset:2048
	ds_read_b128 v[142:145], v142 offset:3072
	s_add_u32 s44, s44, s74
	s_addc_u32 s45, s45, 0
	s_mov_b32 m0, s55
	v_lshl_add_u64 v[202:203], s[44:45], 0, v[174:175]
	ds_read_b128 v[146:149], v228 offset:32768
	ds_read_b128 v[150:153], v228 offset:33792
	ds_read_b128 v[154:157], v228 offset:34816
	ds_read_b128 v[158:161], v228 offset:35840
	ds_read_b128 v[162:165], v228 offset:36864
	ds_read_b128 v[190:193], v228 offset:37888
	ds_read_b128 v[194:197], v228 offset:38912
	ds_read_b128 v[198:201], v228 offset:39936
	global_load_lds_dwordx4 v[202:203], off
	v_lshl_add_u64 v[202:203], s[44:45], 0, v[176:177]
	s_mov_b32 m0, s3
	s_nop 0
	global_load_lds_dwordx4 v[202:203], off
	s_waitcnt lgkmcnt(8)
	s_barrier
	s_waitcnt lgkmcnt(0)
	s_waitcnt lgkmcnt(0)
	v_mfma_f32_16x16x32_bf16 v[124:127], v[130:133], v[146:149], v[124:127]
	v_mfma_f32_16x16x32_bf16 v[120:123], v[138:141], v[146:149], v[120:123]
	v_mfma_f32_16x16x32_bf16 v[112:115], v[130:133], v[154:157], v[112:115]
	v_mfma_f32_16x16x32_bf16 v[104:107], v[138:141], v[154:157], v[104:107]
	v_mfma_f32_16x16x32_bf16 v[96:99], v[130:133], v[162:165], v[96:99]
	v_mfma_f32_16x16x32_bf16 v[88:91], v[138:141], v[162:165], v[88:91]
	v_mfma_f32_16x16x32_bf16 v[80:83], v[130:133], v[194:197], v[80:83]
	v_mfma_f32_16x16x32_bf16 v[72:75], v[138:141], v[194:197], v[72:75]
	v_mfma_f32_16x16x32_bf16 v[124:127], v[134:137], v[150:153], v[124:127]
	v_mfma_f32_16x16x32_bf16 v[120:123], v[142:145], v[150:153], v[120:123]
	v_mfma_f32_16x16x32_bf16 v[112:115], v[134:137], v[158:161], v[112:115]
	v_mfma_f32_16x16x32_bf16 v[104:107], v[142:145], v[158:161], v[104:107]
	v_mfma_f32_16x16x32_bf16 v[96:99], v[134:137], v[190:193], v[96:99]
	v_mfma_f32_16x16x32_bf16 v[88:91], v[142:145], v[190:193], v[88:91]
	v_mfma_f32_16x16x32_bf16 v[80:83], v[134:137], v[198:201], v[80:83]
	v_mfma_f32_16x16x32_bf16 v[72:75], v[142:145], v[198:201], v[72:75]
	s_barrier
	s_add_i32 s44, s46, s57
	v_add_u32_e32 v172, s78, v225
	v_lshl_add_u64 v[166:167], v[166:167], 0, s[88:89]
	s_mov_b32 m0, s44
	ds_read_b128 v[202:205], v172
	ds_read_b128 v[230:233], v172 offset:1024
	ds_read_b128 v[234:237], v172 offset:2048
	ds_read_b128 v[238:241], v172 offset:3072
	global_load_lds_dwordx4 v[166:167], off
	v_lshl_add_u64 v[166:167], v[206:207], 0, s[88:89]
	s_add_i32 m0, s44, 0x2000
	s_nop 0
	global_load_lds_dwordx4 v[166:167], off
	s_barrier
; #define PG8_STAGE(bufoff, gbase, voff) do { _Pragma("unroll") for (int _i = 0; _i < 2; ++_i) \
;         __builtin_amdgcn_global_load_lds((const unsigned*)((const char*)(gbase) + (voff)[_i]), (LAS unsigned*)(lds + (bufoff) + ldsw + _i * 8192), 16, 0, 0); } while (0)
; #define PG8_LDA(dst, b, h) do { _Pragma("unroll") for (int m = 0; m < 4; ++m) _Pragma("unroll") for (int k = 0; k < 2; ++k) dst[m][k] = *(const LAS bf16x8*)(lds + PG8_SA(b, h) + aoff + m * 2048 + k * 1024); } while (0)
; #define PG8_MMA(ai, bj, At, Bt) do { __builtin_amdgcn_s_setprio(1); _Pragma("unroll") for (int m = 0; m < 4; ++m) _Pragma("unroll") for (int n = 0; n < 2; ++n) _Pragma("unroll") for (int k = 0; k < 2; ++k) \
;         acc[ai][bj][m][n] = __builtin_amdgcn_mfma_f32_16x16x32_bf16(Bt[n][k], At[m][k], acc[ai][bj][m][n], 0, 0, 0); __builtin_amdgcn_s_setprio(0); } while (0)
; #define PG8_WAIT_V(n) asm volatile("s_waitcnt vmcnt(" #n ")" ::: "memory")
; #define PG8_WAIT_L(n) asm volatile("s_waitcnt lgkmcnt(" #n ")" ::: "memory")
; #define PG8_BAR __builtin_amdgcn_s_barrier()
; #define PG8_SCHED __builtin_amdgcn_sched_barrier(0)
; template <class Epi>
; __device__ __forceinline__ void gemm_phase(LAS unsigned char* lds, const Gemm g, const StaticOrder& S, const Epi& E) {
;     ...
;             PG8_BAR; PG8_WAIT_L(0); PG8_MMA(0, 1, At, B1); PG8_BAR;
;             PG8_LDA(At, 1, 1); PG8_STAGE(PG8_SA(1, 0), a3, voffA);
;             PG8_BAR; PG8_WAIT_L(0); PG8_MMA(1, 0, At, B0); PG8_BAR; PG8_SCHED;
;             PG8_STAGE(PG8_SB(1, 1), b3 + hstepB, voffB);
;             PG8_WAIT_V(6); PG8_BAR; PG8_MMA(1, 1, At, B1); PG8_BAR;
;         }
	s_waitcnt lgkmcnt(0)
	s_waitcnt lgkmcnt(0)
	v_mfma_f32_16x16x32_bf16 v[116:119], v[202:205], v[146:149], v[116:119]
	v_mfma_f32_16x16x32_bf16 v[108:111], v[234:237], v[146:149], v[108:111]
	v_mfma_f32_16x16x32_bf16 v[100:103], v[202:205], v[154:157], v[100:103]
	v_mfma_f32_16x16x32_bf16 v[92:95], v[234:237], v[154:157], v[92:95]
	v_mfma_f32_16x16x32_bf16 v[84:87], v[202:205], v[162:165], v[84:87]
	v_mfma_f32_16x16x32_bf16 v[76:79], v[234:237], v[162:165], v[76:79]
	v_mfma_f32_16x16x32_bf16 v[68:71], v[202:205], v[194:197], v[68:71]
	v_mfma_f32_16x16x32_bf16 v[64:67], v[234:237], v[194:197], v[64:67]
	v_mfma_f32_16x16x32_bf16 v[116:119], v[230:233], v[150:153], v[116:119]
	v_mfma_f32_16x16x32_bf16 v[108:111], v[238:241], v[150:153], v[108:111]
	v_mfma_f32_16x16x32_bf16 v[100:103], v[230:233], v[158:161], v[100:103]
	v_mfma_f32_16x16x32_bf16 v[92:95], v[238:241], v[158:161], v[92:95]
	v_mfma_f32_16x16x32_bf16 v[84:87], v[230:233], v[190:193], v[84:87]
	v_mfma_f32_16x16x32_bf16 v[76:79], v[238:241], v[190:193], v[76:79]
	v_mfma_f32_16x16x32_bf16 v[68:71], v[230:233], v[198:201], v[68:71]
	v_mfma_f32_16x16x32_bf16 v[64:67], v[238:241], v[198:201], v[64:67]
	s_mov_b32 m0, s60
	v_lshl_add_u64 v[166:167], v[242:243], 0, s[88:89]
	s_barrier
	ds_read_b128 v[146:149], v228 offset:49152
	ds_read_b128 v[150:153], v228 offset:50176
	ds_read_b128 v[154:157], v228 offset:51200
	ds_read_b128 v[158:161], v228 offset:52224
	ds_read_b128 v[162:165], v228 offset:53248
	ds_read_b128 v[190:193], v228 offset:54272
	ds_read_b128 v[194:197], v228 offset:55296
	ds_read_b128 v[198:201], v228 offset:56320
	global_load_lds_dwordx4 v[166:167], off
	v_lshl_add_u64 v[166:167], v[244:245], 0, s[88:89]
	s_mov_b32 m0, s61
	s_nop 0
	global_load_lds_dwordx4 v[166:167], off
	s_barrier
	s_waitcnt lgkmcnt(0)
	s_waitcnt lgkmcnt(0)
	v_mfma_f32_16x16x32_bf16 v[60:63], v[130:133], v[146:149], v[60:63]
	v_mfma_f32_16x16x32_bf16 v[56:59], v[138:141], v[146:149], v[56:59]
	v_mfma_f32_16x16x32_bf16 v[52:55], v[130:133], v[154:157], v[52:55]
	v_mfma_f32_16x16x32_bf16 v[44:47], v[138:141], v[154:157], v[44:47]
	v_mfma_f32_16x16x32_bf16 v[36:39], v[130:133], v[162:165], v[36:39]
	v_mfma_f32_16x16x32_bf16 v[28:31], v[138:141], v[162:165], v[28:31]
	v_mfma_f32_16x16x32_bf16 v[20:23], v[130:133], v[194:197], v[20:23]
	v_mfma_f32_16x16x32_bf16 v[12:15], v[138:141], v[194:197], v[12:15]
	v_mfma_f32_16x16x32_bf16 v[60:63], v[134:137], v[150:153], v[60:63]
	v_mfma_f32_16x16x32_bf16 v[56:59], v[142:145], v[150:153], v[56:59]
	v_mfma_f32_16x16x32_bf16 v[52:55], v[134:137], v[158:161], v[52:55]
	v_mfma_f32_16x16x32_bf16 v[44:47], v[142:145], v[158:161], v[44:47]
	v_mfma_f32_16x16x32_bf16 v[36:39], v[134:137], v[190:193], v[36:39]
	v_mfma_f32_16x16x32_bf16 v[28:31], v[142:145], v[190:193], v[28:31]
	v_mfma_f32_16x16x32_bf16 v[20:23], v[134:137], v[198:201], v[20:23]
	v_mfma_f32_16x16x32_bf16 v[12:15], v[142:145], v[198:201], v[12:15]
	s_barrier
	s_add_i32 s44, s78, s57
	v_lshl_add_u64 v[130:131], v[246:247], 0, s[88:89]
	s_mov_b32 m0, s44
	s_nop 0
	global_load_lds_dwordx4 v[130:131], off
	v_lshl_add_u64 v[130:131], v[248:249], 0, s[88:89]
	s_add_i32 m0, s44, 0x2000
	s_nop 0
	global_load_lds_dwordx4 v[130:131], off
	s_waitcnt vmcnt(6)
	s_barrier
	v_mfma_f32_16x16x32_bf16 v[48:51], v[202:205], v[146:149], v[48:51]
	v_mfma_f32_16x16x32_bf16 v[40:43], v[234:237], v[146:149], v[40:43]
	v_mfma_f32_16x16x32_bf16 v[32:35], v[202:205], v[154:157], v[32:35]
	v_mfma_f32_16x16x32_bf16 v[24:27], v[234:237], v[154:157], v[24:27]
	v_mfma_f32_16x16x32_bf16 v[16:19], v[202:205], v[162:165], v[16:19]
	v_mfma_f32_16x16x32_bf16 v[8:11], v[234:237], v[162:165], v[8:11]
	v_mfma_f32_16x16x32_bf16 v[4:7], v[202:205], v[194:197], v[4:7]
	v_mfma_f32_16x16x32_bf16 v[0:3], v[234:237], v[194:197], v[0:3]
	v_mfma_f32_16x16x32_bf16 v[48:51], v[230:233], v[150:153], v[48:51]
	v_mfma_f32_16x16x32_bf16 v[40:43], v[238:241], v[150:153], v[40:43]
	v_mfma_f32_16x16x32_bf16 v[32:35], v[230:233], v[158:161], v[32:35]
	v_mfma_f32_16x16x32_bf16 v[24:27], v[238:241], v[158:161], v[24:27]
	v_mfma_f32_16x16x32_bf16 v[16:19], v[230:233], v[190:193], v[16:19]
	v_mfma_f32_16x16x32_bf16 v[8:11], v[238:241], v[190:193], v[8:11]
	v_mfma_f32_16x16x32_bf16 v[4:7], v[230:233], v[198:201], v[4:7]
	v_mfma_f32_16x16x32_bf16 v[0:3], v[238:241], v[198:201], v[0:3]
	s_add_u32 s36, s36, 0x100
	s_addc_u32 s37, s37, 0
	s_add_u32 s69, s69, 0x100
	s_addc_u32 s70, s70, 0
	s_cmp_ge_u32 s35, s16
	s_mov_b32 s44, s35
	s_barrier
	s_cbranch_scc1 .LBB0_119

; #define PG8_WAIT_V(n) asm volatile("s_waitcnt vmcnt(" #n ")" ::: "memory")
; #define PG8_BAR __builtin_amdgcn_s_barrier()
; template <class Epi>
; __device__ __forceinline__ void gemm_phase(LAS unsigned char* lds, const Gemm g, const StaticOrder& S, const Epi& E) {
;     ...
;     PG8_WAIT_V(0);
;     if (wr == 0) PG8_BAR;
;     PG8_BAR;
.LBB0_354:
	s_setprio 0
	s_waitcnt vmcnt(0)
	s_cmpk_gt_u32 s79, 0xff
	s_cbranch_scc1 .LBB0_94
	s_barrier
	s_branch .LBB0_94
